# conv_tile: each wave converts 8 consecutive k rows so the transposed LDS image is written with 4 ds_write_b128 (v_cvt_pk_bf16_f32 packing) instead of 32 bank-conflicting ds_write_b16; prep_unit f32-MF
# speedup vs baseline: 1.0246x; 1.0069x over previous
; #define LAS __attribute__((address_space(3)))
; __device__ __forceinline__ void conv_tile(LAS unsigned char* lds, const float* __restrict__ src, int Nsrc, bf16_t* __restrict__ dst, int K, int type, const float* __restrict__ ksc, int kt, int nt) {
;     LAS bf16_t* tile = (LAS bf16_t*)lds;
;     int tid = threadIdx.x; asm volatile("" : "+v"(tid));
;     const int n4 = (tid & 63) * 4, kr = tid >> 6;
;     const int sc = wsrc_col(type, nt * 256 + n4);
;     f32x4 v[8];
; #pragma unroll
;     for (int i = 0; i < 8; ++i) { const int k = kt * 64 + kr + 8 * i; v[i] = (f32x4){0.f, 0.f, 0.f, 0.f};
;         if (sc >= 0) { v[i] = *(const f32x4*)(src + (size_t)k * Nsrc + sc); if (ksc) v[i] *= ksc[k]; } }
.LBB0_68:
	s_mul_i32 s38, s38, s40
	s_sub_i32 s0, s3, s38
	s_lshl_b32 s38, s0, 6
	s_cmp_lg_u64 s[68:69], 0
	s_cselect_b64 s[0:1], -1, 0
	v_ashrrev_i32_e32 v38, 6, v36
	v_cndmask_b32_e64 v1, 0, 1, s[0:1]
	v_cmp_lt_i32_e64 s[40:41], -1, v208
	v_lshl_add_u32 v32, v38, 3, s38
	v_lshl_add_u64 v[34:35], v[208:209], 2, s[70:71]
	v_mov_b32_e32 v0, 0
	v_cmp_ne_u32_e64 s[0:1], 1, v1
	v_mov_b32_e32 v4, 0
	v_mov_b32_e32 v5, 0
	v_mov_b32_e32 v6, 0
	v_mov_b32_e32 v7, 0
	s_and_saveexec_b64 s[70:71], s[40:41]
	s_cbranch_execz .LBB0_71
	v_ashrrev_i32_e32 v33, 31, v32
	v_mul_lo_u32 v1, s29, v32
	v_mul_lo_u32 v4, s28, v33
	v_mad_u64_u32 v[2:3], s[34:35], s28, v32, 0
	v_add3_u32 v3, v3, v4, v1
	v_lshl_add_u64 v[2:3], v[2:3], 2, v[34:35]
	global_load_dwordx4 v[4:7], v[2:3], off
	s_and_b64 vcc, exec, s[0:1]
	s_cbranch_vccnz .LBB0_71
	v_lshl_add_u64 v[2:3], v[32:33], 2, s[68:69]
	global_load_dword v2, v[2:3], off
	s_waitcnt vmcnt(0)
	v_pk_mul_f32 v[6:7], v[6:7], v[2:3] op_sel_hi:[1,0]
	v_pk_mul_f32 v[4:5], v[4:5], v[2:3] op_sel_hi:[1,0]
.LBB0_71:
	s_or_b64 exec, exec, s[70:71]
	v_mov_b32_e32 v1, 0
	v_mov_b32_e32 v2, 0
	v_mov_b32_e32 v3, 0
	s_and_saveexec_b64 s[70:71], s[40:41]
	s_cbranch_execz .LBB0_74
	v_add_u32_e32 v0, 1, v32
	v_ashrrev_i32_e32 v1, 31, v0
	v_mul_lo_u32 v2, s28, v1
	v_mul_lo_u32 v3, s29, v0
	v_mad_u64_u32 v[0:1], s[34:35], s28, v0, 0
	v_add3_u32 v1, v1, v2, v3
	v_lshl_add_u64 v[0:1], v[0:1], 2, v[34:35]
	global_load_dwordx4 v[0:3], v[0:1], off
	s_and_b64 vcc, exec, s[0:1]
	s_cbranch_vccnz .LBB0_74
	v_ashrrev_i32_e32 v33, 31, v32
	v_lshl_add_u64 v[8:9], v[32:33], 2, s[68:69]
	global_load_dword v8, v[8:9], off offset:4
	s_waitcnt vmcnt(0)
	v_pk_mul_f32 v[2:3], v[2:3], v[8:9] op_sel_hi:[1,0]
	v_pk_mul_f32 v[0:1], v[0:1], v[8:9] op_sel_hi:[1,0]
.LBB0_74:
	s_or_b64 exec, exec, s[70:71]
	v_mov_b32_e32 v8, 0
	v_mov_b32_e32 v12, 0
	v_mov_b32_e32 v13, 0
	v_mov_b32_e32 v14, 0
	v_mov_b32_e32 v15, 0
	s_and_saveexec_b64 s[70:71], s[40:41]
	s_cbranch_execz .LBB0_77
	v_add_u32_e32 v9, 2, v32
	v_ashrrev_i32_e32 v10, 31, v9
	v_mul_lo_u32 v12, s28, v10
	v_mul_lo_u32 v13, s29, v9
	v_mad_u64_u32 v[10:11], s[34:35], s28, v9, 0
	v_add3_u32 v11, v11, v12, v13
	v_lshl_add_u64 v[10:11], v[10:11], 2, v[34:35]
	global_load_dwordx4 v[12:15], v[10:11], off
	s_and_b64 vcc, exec, s[0:1]
	s_cbranch_vccnz .LBB0_77
	v_ashrrev_i32_e32 v33, 31, v32
	v_lshl_add_u64 v[10:11], v[32:33], 2, s[68:69]
	global_load_dword v10, v[10:11], off offset:8
	s_waitcnt vmcnt(0)
	v_pk_mul_f32 v[14:15], v[14:15], v[10:11] op_sel_hi:[1,0]
	v_pk_mul_f32 v[12:13], v[12:13], v[10:11] op_sel_hi:[1,0]
.LBB0_77:
	s_or_b64 exec, exec, s[70:71]
	v_mov_b32_e32 v9, 0
	v_mov_b32_e32 v10, 0
	v_mov_b32_e32 v11, 0
	s_and_saveexec_b64 s[70:71], s[40:41]
	s_cbranch_execz .LBB0_80
	v_add_u32_e32 v8, 3, v32
	v_ashrrev_i32_e32 v9, 31, v8
	v_mul_lo_u32 v10, s28, v9
	v_mul_lo_u32 v11, s29, v8
	v_mad_u64_u32 v[8:9], s[34:35], s28, v8, 0
	v_add3_u32 v9, v9, v10, v11
	v_lshl_add_u64 v[8:9], v[8:9], 2, v[34:35]
	global_load_dwordx4 v[8:11], v[8:9], off
	s_and_b64 vcc, exec, s[0:1]
	s_cbranch_vccnz .LBB0_80
	v_ashrrev_i32_e32 v33, 31, v32
	v_lshl_add_u64 v[16:17], v[32:33], 2, s[68:69]
	global_load_dword v16, v[16:17], off offset:12
	s_waitcnt vmcnt(0)
	v_pk_mul_f32 v[10:11], v[10:11], v[16:17] op_sel_hi:[1,0]
	v_pk_mul_f32 v[8:9], v[8:9], v[16:17] op_sel_hi:[1,0]
.LBB0_80:
	s_or_b64 exec, exec, s[70:71]
	v_mov_b32_e32 v16, 0
	v_mov_b32_e32 v20, 0
	v_mov_b32_e32 v21, 0
	v_mov_b32_e32 v22, 0
	v_mov_b32_e32 v23, 0
	s_and_saveexec_b64 s[70:71], s[40:41]
	s_cbranch_execz .LBB0_83
	v_add_u32_e32 v17, 4, v32
	v_ashrrev_i32_e32 v18, 31, v17
	v_mul_lo_u32 v20, s28, v18
	v_mul_lo_u32 v21, s29, v17
	v_mad_u64_u32 v[18:19], s[34:35], s28, v17, 0
	v_add3_u32 v19, v19, v20, v21
	v_lshl_add_u64 v[18:19], v[18:19], 2, v[34:35]
	global_load_dwordx4 v[20:23], v[18:19], off
	s_and_b64 vcc, exec, s[0:1]
	s_cbranch_vccnz .LBB0_83
	v_ashrrev_i32_e32 v33, 31, v32
	v_lshl_add_u64 v[18:19], v[32:33], 2, s[68:69]
	global_load_dword v18, v[18:19], off offset:16
	s_waitcnt vmcnt(0)
	v_pk_mul_f32 v[22:23], v[22:23], v[18:19] op_sel_hi:[1,0]
	v_pk_mul_f32 v[20:21], v[20:21], v[18:19] op_sel_hi:[1,0]
.LBB0_83:
	s_or_b64 exec, exec, s[70:71]
	v_mov_b32_e32 v17, 0
	v_mov_b32_e32 v18, 0
	v_mov_b32_e32 v19, 0
	s_and_saveexec_b64 s[70:71], s[40:41]
	s_cbranch_execz .LBB0_86
	v_add_u32_e32 v16, 5, v32
	v_ashrrev_i32_e32 v17, 31, v16
	v_mul_lo_u32 v18, s28, v17
	v_mul_lo_u32 v19, s29, v16
	v_mad_u64_u32 v[16:17], s[34:35], s28, v16, 0
	v_add3_u32 v17, v17, v18, v19
	v_lshl_add_u64 v[16:17], v[16:17], 2, v[34:35]
	global_load_dwordx4 v[16:19], v[16:17], off
	s_and_b64 vcc, exec, s[0:1]
	s_cbranch_vccnz .LBB0_86
	v_ashrrev_i32_e32 v33, 31, v32
	v_lshl_add_u64 v[24:25], v[32:33], 2, s[68:69]
	global_load_dword v24, v[24:25], off offset:20
	s_waitcnt vmcnt(0)
	v_pk_mul_f32 v[18:19], v[18:19], v[24:25] op_sel_hi:[1,0]
	v_pk_mul_f32 v[16:17], v[16:17], v[24:25] op_sel_hi:[1,0]
; #define LAS __attribute__((address_space(3)))
; __device__ __forceinline__ bf16_t f2bf(float f) { unsigned u = __float_as_uint(f); u += 0x7FFFu + ((u >> 16) & 1u); return (bf16_t)(u >> 16); }
; __device__ __forceinline__ void conv_tile(LAS unsigned char* lds, const float* __restrict__ src, int Nsrc, bf16_t* __restrict__ dst, int K, int type, const float* __restrict__ ksc, int kt, int nt) {
;     ...
;     for (int i = 0; i < 8; ++i) { const int k = kt * 64 + kr + 8 * i; v[i] = (f32x4){0.f, 0.f, 0.f, 0.f};
;         if (sc >= 0) { v[i] = *(const f32x4*)(src + (size_t)k * Nsrc + sc); if (ksc) v[i] *= ksc[k]; } }
; #pragma unroll
;     for (int i = 0; i < 8; ++i) {
; #pragma unroll
;         for (int j = 0; j < 4; ++j) tile[(n4 + j) * 72 + kr + 8 * i] = f2bf(v[i][j]); }
;     __syncthreads();
; #pragma unroll
;     for (int e = 0; e < 4; ++e) { const int id = tid + e * NTHR, n2 = id >> 3, kc = id & 7;
;         const u32x4 w = *(const LAS u32x4*)(tile + n2 * 72 + kc * 8);
;         *(u32x4*)(dst + (size_t)(nt * 256 + n2) * K + kt * 64 + kc * 8) = w; }
;     __syncthreads();
.LBB0_86:
	s_or_b64 exec, exec, s[70:71]
	v_mov_b32_e32 v24, 0
	v_mov_b32_e32 v28, 0
	v_mov_b32_e32 v29, 0
	v_mov_b32_e32 v30, 0
	v_mov_b32_e32 v31, 0
	s_and_saveexec_b64 s[70:71], s[40:41]
	s_cbranch_execz .LBB0_89
	v_add_u32_e32 v25, 6, v32
	v_ashrrev_i32_e32 v26, 31, v25
	v_mul_lo_u32 v28, s28, v26
	v_mul_lo_u32 v29, s29, v25
	v_mad_u64_u32 v[26:27], s[34:35], s28, v25, 0
	v_add3_u32 v27, v27, v28, v29
	v_lshl_add_u64 v[26:27], v[26:27], 2, v[34:35]
	global_load_dwordx4 v[28:31], v[26:27], off
	s_and_b64 vcc, exec, s[0:1]
	s_cbranch_vccnz .LBB0_89
	v_ashrrev_i32_e32 v33, 31, v32
	v_lshl_add_u64 v[26:27], v[32:33], 2, s[68:69]
	global_load_dword v26, v[26:27], off offset:24
	s_waitcnt vmcnt(0)
	v_pk_mul_f32 v[30:31], v[30:31], v[26:27] op_sel_hi:[1,0]
	v_pk_mul_f32 v[28:29], v[28:29], v[26:27] op_sel_hi:[1,0]
.LBB0_89:
	s_or_b64 exec, exec, s[70:71]
	v_mov_b32_e32 v25, 0
	v_mov_b32_e32 v26, 0
	v_mov_b32_e32 v27, 0
	s_and_saveexec_b64 s[70:71], s[40:41]
	s_cbranch_execz .LBB0_92
	v_add_u32_e32 v24, 7, v32
	v_ashrrev_i32_e32 v25, 31, v24
	v_mul_lo_u32 v26, s28, v25
	v_mul_lo_u32 v27, s29, v24
	v_mad_u64_u32 v[24:25], s[28:29], s28, v24, 0
	v_add3_u32 v25, v25, v26, v27
	v_lshl_add_u64 v[24:25], v[24:25], 2, v[34:35]
	global_load_dwordx4 v[24:27], v[24:25], off
	s_and_b64 vcc, exec, s[0:1]
	s_cbranch_vccnz .LBB0_92
	v_ashrrev_i32_e32 v33, 31, v32
	v_lshl_add_u64 v[32:33], v[32:33], 2, s[68:69]
	global_load_dword v32, v[32:33], off offset:28
	s_waitcnt vmcnt(0)
	v_pk_mul_f32 v[26:27], v[26:27], v[32:33] op_sel_hi:[1,0]
	v_pk_mul_f32 v[24:25], v[24:25], v[32:33] op_sel_hi:[1,0]
.LBB0_92:
	s_or_b64 exec, exec, s[70:71]
	s_waitcnt vmcnt(0)
	v_lshlrev_b32_e32 v32, 4, v38
	v_mul_u32_u24_e32 v33, 0x90, v37
	v_add3_u32 v32, 0, v32, v33
	v_cvt_pk_bf16_f32 v40, v4, v0
	v_cvt_pk_bf16_f32 v41, v12, v8
	v_cvt_pk_bf16_f32 v42, v20, v16
	v_cvt_pk_bf16_f32 v43, v28, v24
	ds_write_b128 v32, v[40:43]
	v_cvt_pk_bf16_f32 v44, v5, v1
	v_cvt_pk_bf16_f32 v45, v13, v9
	v_cvt_pk_bf16_f32 v46, v21, v17
	v_cvt_pk_bf16_f32 v47, v29, v25
	ds_write_b128 v32, v[44:47] offset:144
	v_cvt_pk_bf16_f32 v48, v6, v2
	v_cvt_pk_bf16_f32 v49, v14, v10
	v_cvt_pk_bf16_f32 v50, v22, v18
	v_cvt_pk_bf16_f32 v51, v30, v26
	ds_write_b128 v32, v[48:51] offset:288
	v_cvt_pk_bf16_f32 v52, v7, v3
	v_cvt_pk_bf16_f32 v53, v15, v11
	v_cvt_pk_bf16_f32 v54, v23, v19
	v_cvt_pk_bf16_f32 v55, v31, v27
	ds_write_b128 v32, v[52:55] offset:432
	s_ashr_i32 s39, s38, 31
	v_lshlrev_b32_e32 v0, 4, v36
	s_lshl_b64 s[0:1], s[38:39], 1
	v_and_b32_e32 v208, 0x70, v0
	s_add_u32 s0, s26, s0
	v_add_u32_e32 v8, 0, v208
	s_addc_u32 s1, s27, s1
	v_ashrrev_i32_e32 v4, 3, v36
	v_lshl_add_u64 v[10:11], s[0:1], 0, v[208:209]
	v_mad_u64_u32 v[0:1], s[0:1], v4, s87, v[8:9]
	v_add_u32_e32 v4, s76, v4
	v_ashrrev_i32_e32 v7, 31, v4
	v_mad_u64_u32 v[4:5], s[0:1], v4, s31, 0
	v_mov_b32_e32 v6, v5
	s_waitcnt lgkmcnt(0)
	s_barrier
	ds_read_b128 v[0:3], v0
	v_mad_u64_u32 v[6:7], s[0:1], v7, s31, v[6:7]
	v_mov_b32_e32 v5, v6
	v_lshl_add_u64 v[12:13], v[4:5], 1, v[10:11]
	v_add_u32_e32 v4, 0x200, v36
	v_ashrrev_i32_e32 v9, 3, v4
	v_mad_u64_u32 v[4:5], s[0:1], v9, s87, v[8:9]
	ds_read_b128 v[4:7], v4
	s_waitcnt lgkmcnt(1)
	global_store_dwordx4 v[12:13], v[0:3], off
	s_mov_b64 s[38:39], 0
	s_nop 0
	v_add_u32_e32 v0, s76, v9
	v_ashrrev_i32_e32 v3, 31, v0
	v_mad_u64_u32 v[0:1], s[0:1], v0, s31, 0
	v_mov_b32_e32 v2, v1
	v_mad_u64_u32 v[2:3], s[0:1], v3, s31, v[2:3]
	v_mov_b32_e32 v1, v2
	v_lshl_add_u64 v[0:1], v[0:1], 1, v[10:11]
	s_waitcnt lgkmcnt(0)
	global_store_dwordx4 v[0:1], v[4:7], off
	v_add_u32_e32 v0, 0x400, v36
	s_nop 0
	v_ashrrev_i32_e32 v4, 3, v0
	v_mad_u64_u32 v[0:1], s[0:1], v4, s87, v[8:9]
	v_add_u32_e32 v4, s76, v4
	v_ashrrev_i32_e32 v7, 31, v4
	v_mad_u64_u32 v[4:5], s[0:1], v4, s31, 0
	v_mov_b32_e32 v6, v5
	ds_read_b128 v[0:3], v0
	v_mad_u64_u32 v[6:7], s[0:1], v7, s31, v[6:7]
	v_mov_b32_e32 v5, v6
	v_lshl_add_u64 v[12:13], v[4:5], 1, v[10:11]
	v_add_u32_e32 v4, 0x600, v36
	v_ashrrev_i32_e32 v9, 3, v4
	v_mad_u64_u32 v[4:5], s[0:1], v9, s87, v[8:9]
	ds_read_b128 v[4:7], v4
	s_waitcnt lgkmcnt(1)
	global_store_dwordx4 v[12:13], v[0:3], off
	s_nop 1
	v_add_u32_e32 v0, s76, v9
	v_ashrrev_i32_e32 v3, 31, v0
	v_mad_u64_u32 v[0:1], s[0:1], v0, s31, 0
	v_mov_b32_e32 v2, v1
	v_mad_u64_u32 v[2:3], s[0:1], v3, s31, v[2:3]
	v_mov_b32_e32 v1, v2
	v_lshl_add_u64 v[0:1], v[0:1], 1, v[10:11]
	s_waitcnt lgkmcnt(0)
	global_store_dwordx4 v[0:1], v[4:7], off
	s_barrier

; #define LAS __attribute__((address_space(3)))
; __device__ __forceinline__ void prep_unit(LAS unsigned char* lds, const Params& p, int l, int unit) {
;     ...
;     for (int tt = 0; tt < 2; ++tt) { const int ti = wid * 2 + tt, it = ti >> 2, jt = ti & 3;
;         f32x4 aKK = {0.f, 0.f, 0.f, 0.f}, aQK = {0.f, 0.f, 0.f, 0.f};
;         if (jt <= it) {
;             const LAS float* pk = Xk + (16 * it + (lane & 15)) * XS + (lane >> 4); const LAS float* pq = Xq + (16 * it + (lane & 15)) * XS + (lane >> 4);
;             const LAS float* pb = Xk + (16 * jt + (lane & 15)) * XS + (lane >> 4);
; #pragma unroll 8
;             for (int d = 0; d < 128; d += 4) { const float ak = pk[d], aq = pq[d], bk = pb[d];
;                 aKK = __builtin_amdgcn_mfma_f32_16x16x4f32(ak, bk, aKK, 0, 0, 0); aQK = __builtin_amdgcn_mfma_f32_16x16x4f32(aq, bk, aQK, 0, 0, 0); }
;         }
.LBB0_631:
	v_or_b32_e32 v0, s31, v24
	v_mov_b32_e32 v3, 0
	v_cmp_le_i32_e32 vcc, v0, v23
	v_lshl_or_b32 v39, v0, 4, v18
	v_mov_b32_e32 v2, v3
	v_mov_b32_e32 v1, v3
	v_mov_b32_e32 v0, v3
	v_mov_b32_e32 v7, v3
	v_mov_b32_e32 v6, v3
	v_mov_b32_e32 v5, v3
	v_mov_b32_e32 v4, v3
	s_and_saveexec_b64 s[28:29], vcc
	s_cbranch_execz .LBB0_634
	s_movk_i32 s31, 0x210
	v_mov_b32_e32 v0, 0
	v_mad_u32_u24 v16, v39, s31, v37
	s_mov_b32 s31, -4
	v_mov_b32_e32 v17, v38
	v_mov_b32_e32 v1, v0
	v_mov_b32_e32 v2, v0
	v_mov_b32_e32 v3, v0
	v_mov_b32_e32 v4, v0
	v_mov_b32_e32 v5, v0
	v_mov_b32_e32 v6, v0
	v_mov_b32_e32 v7, v0
	v_add_u32_e32 v46, 0x8400, v17
	ds_read2_b32 v[40:41], v17 offset1:4
	ds_read2_b32 v[42:43], v16 offset1:4
	ds_read2_b32 v[44:45], v46 offset1:4
.LBB0_633:
	ds_read2_b32 v[130:131], v17 offset0:8 offset1:12
	ds_read2_b32 v[132:133], v16 offset0:8 offset1:12
	ds_read2_b32 v[134:135], v46 offset0:8 offset1:12
	s_add_i32 s31, s31, 32
	s_cmpk_lt_u32 s31, 0x7c
	s_waitcnt lgkmcnt(3)
	v_mfma_f32_16x16x4_f32 v[4:7], v40, v42, v[4:7]
	v_mfma_f32_16x16x4_f32 v[0:3], v44, v42, v[0:3]
	v_mfma_f32_16x16x4_f32 v[4:7], v41, v43, v[4:7]
	v_mfma_f32_16x16x4_f32 v[0:3], v45, v43, v[0:3]
	ds_read2_b32 v[40:41], v17 offset0:16 offset1:20
	ds_read2_b32 v[42:43], v16 offset0:16 offset1:20
	ds_read2_b32 v[44:45], v46 offset0:16 offset1:20
	s_waitcnt lgkmcnt(3)
	v_mfma_f32_16x16x4_f32 v[4:7], v130, v132, v[4:7]
	v_mfma_f32_16x16x4_f32 v[0:3], v134, v132, v[0:3]
	v_mfma_f32_16x16x4_f32 v[4:7], v131, v133, v[4:7]
	v_mfma_f32_16x16x4_f32 v[0:3], v135, v133, v[0:3]
	ds_read2_b32 v[130:131], v17 offset0:24 offset1:28
	ds_read2_b32 v[132:133], v16 offset0:24 offset1:28
	ds_read2_b32 v[134:135], v46 offset0:24 offset1:28
	s_waitcnt lgkmcnt(3)
	v_mfma_f32_16x16x4_f32 v[4:7], v40, v42, v[4:7]
	v_mfma_f32_16x16x4_f32 v[0:3], v44, v42, v[0:3]
	v_mfma_f32_16x16x4_f32 v[4:7], v41, v43, v[4:7]
	v_mfma_f32_16x16x4_f32 v[0:3], v45, v43, v[0:3]
	v_add_u32_e32 v16, 0x80, v16
	v_add_u32_e32 v17, 0x80, v17
	v_add_u32_e32 v46, 0x8400, v17
	ds_read2_b32 v[40:41], v17 offset1:4
	ds_read2_b32 v[42:43], v16 offset1:4
	ds_read2_b32 v[44:45], v46 offset1:4
	s_waitcnt lgkmcnt(3)
	v_mfma_f32_16x16x4_f32 v[4:7], v130, v132, v[4:7]
	v_mfma_f32_16x16x4_f32 v[0:3], v134, v132, v[0:3]
	v_mfma_f32_16x16x4_f32 v[4:7], v131, v133, v[4:7]
	v_mfma_f32_16x16x4_f32 v[0:3], v135, v133, v[0:3]
	s_cbranch_scc1 .LBB0_633
	s_waitcnt lgkmcnt(0)

; #define LAS __attribute__((address_space(3)))
; __device__ __forceinline__ void prep_unit(LAS unsigned char* lds, const Params& p, int l, int unit) {
;     ...
;       for (int I = 0; I < 4; ++I) {
;           f32x4 a0 = {0.f, 0.f, 0.f, 0.f}, a1 = {0.f, 0.f, 0.f, 0.f};
;           const LAS float* pa = Lm + (16 * I + li) * 64 + lq;
; #pragma unroll 4
;           for (int kk = 0; kk < 16 * I; kk += 4) { const float av = pa[kk];
;               a0 = __builtin_amdgcn_mfma_f32_16x16x4f32(av, Xb0[(kk + lq) * XS + li], a0, 0, 0, 0);
;               a1 = __builtin_amdgcn_mfma_f32_16x16x4f32(av, Xb1[(kk + lq) * XS + li], a1, 0, 0, 0); }
.LBB0_655:
	s_lshl_b32 s1, s0, 4
	s_cmp_eq_u32 s0, 0
	s_cbranch_scc1 .LBB0_653
	v_mov_b32_e32 v0, 0
	s_mov_b32 s3, 0
	v_mov_b32_e32 v32, v31
	v_mov_b32_e32 v33, v30
	v_mov_b32_e32 v34, v29
	v_mov_b32_e32 v1, v0
	v_mov_b32_e32 v2, v0
	v_mov_b32_e32 v3, v0
	v_mov_b32_e32 v4, v0
	v_mov_b32_e32 v5, v0
	v_mov_b32_e32 v6, v0
	v_mov_b32_e32 v7, v0
	ds_read_b32 v35, v32
	ds_read_b32 v36, v34
	ds_read_b32 v130, v33
	v_add_u32_e32 v32, 16, v32
	v_add_u32_e32 v34, 0x840, v34
	v_add_u32_e32 v33, 0x840, v33
.LBB0_657:
	ds_read_b32 v131, v32
	ds_read_b32 v132, v34
	ds_read_b32 v133, v33
	v_add_u32_e32 v32, 16, v32
	v_add_u32_e32 v34, 0x840, v34
	v_add_u32_e32 v33, 0x840, v33
	s_waitcnt lgkmcnt(3)
	v_mfma_f32_16x16x4_f32 v[4:7], v35, v36, v[4:7]
	v_mfma_f32_16x16x4_f32 v[0:3], v35, v130, v[0:3]
	ds_read_b32 v35, v32
	ds_read_b32 v36, v34
	ds_read_b32 v130, v33
	v_add_u32_e32 v32, 16, v32
	v_add_u32_e32 v34, 0x840, v34
	v_add_u32_e32 v33, 0x840, v33
	s_add_i32 s3, s3, 8
	s_cmp_ge_u32 s3, s1
	s_waitcnt lgkmcnt(3)
	v_mfma_f32_16x16x4_f32 v[4:7], v131, v132, v[4:7]
	v_mfma_f32_16x16x4_f32 v[0:3], v131, v133, v[0:3]
	s_cbranch_scc0 .LBB0_657
	s_waitcnt lgkmcnt(0)
	s_branch .LBB0_654

; #define LAS __attribute__((address_space(3)))
; __device__ __forceinline__ void conv_tile(LAS unsigned char* lds, const float* __restrict__ src, int Nsrc, bf16_t* __restrict__ dst, int K, int type, const float* __restrict__ ksc, int kt, int nt) {
;     LAS bf16_t* tile = (LAS bf16_t*)lds;
;     int tid = threadIdx.x; asm volatile("" : "+v"(tid));
;     const int n4 = (tid & 63) * 4, kr = tid >> 6;
;     const int sc = wsrc_col(type, nt * 256 + n4);
;     f32x4 v[8];
; #pragma unroll
;     for (int i = 0; i < 8; ++i) { const int k = kt * 64 + kr + 8 * i; v[i] = (f32x4){0.f, 0.f, 0.f, 0.f};
;         if (sc >= 0) { v[i] = *(const f32x4*)(src + (size_t)k * Nsrc + sc); if (ksc) v[i] *= ksc[k]; } }
.LBB0_931:
	s_mul_i32 s71, s71, s70
	s_sub_i32 s34, s3, s71
	s_lshl_b32 s68, s34, 6
	s_cmp_lg_u64 s[64:65], 0
	v_lshl_add_u64 v[34:35], v[208:209], 2, s[40:41]
	s_cselect_b64 s[40:41], -1, 0
	v_ashrrev_i32_e32 v38, 6, v36
	v_cndmask_b32_e64 v1, 0, 1, s[40:41]
	v_cmp_lt_i32_e64 s[0:1], -1, v208
	v_lshl_add_u32 v32, v38, 3, s68
	v_mov_b32_e32 v0, 0
	v_cmp_ne_u32_e64 s[40:41], 1, v1
	v_mov_b32_e32 v4, 0
	v_mov_b32_e32 v5, 0
	v_mov_b32_e32 v6, 0
	v_mov_b32_e32 v7, 0
	s_and_saveexec_b64 s[70:71], s[0:1]
	s_cbranch_execz .LBB0_934
	v_mad_i64_i32 v[2:3], s[78:79], s38, v32, 0
	v_lshl_add_u64 v[2:3], v[2:3], 2, v[34:35]
	global_load_dwordx4 v[4:7], v[2:3], off
	s_and_b64 vcc, exec, s[40:41]
	s_cbranch_vccnz .LBB0_934
	v_ashrrev_i32_e32 v33, 31, v32
	v_lshl_add_u64 v[2:3], v[32:33], 2, s[64:65]
	global_load_dword v2, v[2:3], off
	s_waitcnt vmcnt(0)
	v_pk_mul_f32 v[6:7], v[6:7], v[2:3] op_sel_hi:[1,0]
	v_pk_mul_f32 v[4:5], v[4:5], v[2:3] op_sel_hi:[1,0]
.LBB0_934:
	s_or_b64 exec, exec, s[70:71]
	v_mov_b32_e32 v1, 0
	v_mov_b32_e32 v2, 0
	v_mov_b32_e32 v3, 0
	s_and_saveexec_b64 s[70:71], s[0:1]
	s_cbranch_execz .LBB0_937
	v_add_u32_e32 v0, 1, v32
	v_mad_i64_i32 v[0:1], s[78:79], s38, v0, 0
	v_lshl_add_u64 v[0:1], v[0:1], 2, v[34:35]
	global_load_dwordx4 v[0:3], v[0:1], off
	s_and_b64 vcc, exec, s[40:41]
	s_cbranch_vccnz .LBB0_937
	v_ashrrev_i32_e32 v33, 31, v32
	v_lshl_add_u64 v[8:9], v[32:33], 2, s[64:65]
	global_load_dword v8, v[8:9], off offset:4
	s_waitcnt vmcnt(0)
	v_pk_mul_f32 v[2:3], v[2:3], v[8:9] op_sel_hi:[1,0]
	v_pk_mul_f32 v[0:1], v[0:1], v[8:9] op_sel_hi:[1,0]
.LBB0_937:
	s_or_b64 exec, exec, s[70:71]
	v_mov_b32_e32 v8, 0
	v_mov_b32_e32 v12, 0
	v_mov_b32_e32 v13, 0
	v_mov_b32_e32 v14, 0
	v_mov_b32_e32 v15, 0
	s_and_saveexec_b64 s[70:71], s[0:1]
	s_cbranch_execz .LBB0_940
	v_add_u32_e32 v9, 2, v32
	v_mad_i64_i32 v[10:11], s[78:79], s38, v9, 0
	v_lshl_add_u64 v[10:11], v[10:11], 2, v[34:35]
	global_load_dwordx4 v[12:15], v[10:11], off
	s_and_b64 vcc, exec, s[40:41]
	s_cbranch_vccnz .LBB0_940
	v_ashrrev_i32_e32 v33, 31, v32
	v_lshl_add_u64 v[10:11], v[32:33], 2, s[64:65]
	global_load_dword v10, v[10:11], off offset:8
	s_waitcnt vmcnt(0)
	v_pk_mul_f32 v[14:15], v[14:15], v[10:11] op_sel_hi:[1,0]
	v_pk_mul_f32 v[12:13], v[12:13], v[10:11] op_sel_hi:[1,0]
.LBB0_940:
	s_or_b64 exec, exec, s[70:71]
	v_mov_b32_e32 v9, 0
	v_mov_b32_e32 v10, 0
	v_mov_b32_e32 v11, 0
	s_and_saveexec_b64 s[70:71], s[0:1]
	s_cbranch_execz .LBB0_943
	v_add_u32_e32 v8, 3, v32
	v_mad_i64_i32 v[8:9], s[78:79], s38, v8, 0
	v_lshl_add_u64 v[8:9], v[8:9], 2, v[34:35]
	global_load_dwordx4 v[8:11], v[8:9], off
	s_and_b64 vcc, exec, s[40:41]
	s_cbranch_vccnz .LBB0_943
	v_ashrrev_i32_e32 v33, 31, v32
	v_lshl_add_u64 v[16:17], v[32:33], 2, s[64:65]
	global_load_dword v16, v[16:17], off offset:12
	s_waitcnt vmcnt(0)
	v_pk_mul_f32 v[10:11], v[10:11], v[16:17] op_sel_hi:[1,0]
	v_pk_mul_f32 v[8:9], v[8:9], v[16:17] op_sel_hi:[1,0]
.LBB0_943:
	s_or_b64 exec, exec, s[70:71]
	v_mov_b32_e32 v16, 0
	v_mov_b32_e32 v20, 0
	v_mov_b32_e32 v21, 0
	v_mov_b32_e32 v22, 0
	v_mov_b32_e32 v23, 0
	s_and_saveexec_b64 s[70:71], s[0:1]
	s_cbranch_execz .LBB0_946
	v_add_u32_e32 v17, 4, v32
	v_mad_i64_i32 v[18:19], s[78:79], s38, v17, 0
	v_lshl_add_u64 v[18:19], v[18:19], 2, v[34:35]
	global_load_dwordx4 v[20:23], v[18:19], off
	s_and_b64 vcc, exec, s[40:41]
	s_cbranch_vccnz .LBB0_946
	v_ashrrev_i32_e32 v33, 31, v32
	v_lshl_add_u64 v[18:19], v[32:33], 2, s[64:65]
	global_load_dword v18, v[18:19], off offset:16
	s_waitcnt vmcnt(0)
	v_pk_mul_f32 v[22:23], v[22:23], v[18:19] op_sel_hi:[1,0]
	v_pk_mul_f32 v[20:21], v[20:21], v[18:19] op_sel_hi:[1,0]
.LBB0_946:
	s_or_b64 exec, exec, s[70:71]
	v_mov_b32_e32 v17, 0
	v_mov_b32_e32 v18, 0
	v_mov_b32_e32 v19, 0
	s_and_saveexec_b64 s[70:71], s[0:1]
	s_cbranch_execz .LBB0_949
	v_add_u32_e32 v16, 5, v32
	v_mad_i64_i32 v[16:17], s[78:79], s38, v16, 0
	v_lshl_add_u64 v[16:17], v[16:17], 2, v[34:35]
	global_load_dwordx4 v[16:19], v[16:17], off
	s_and_b64 vcc, exec, s[40:41]
	s_cbranch_vccnz .LBB0_949
	v_ashrrev_i32_e32 v33, 31, v32
	v_lshl_add_u64 v[24:25], v[32:33], 2, s[64:65]
	global_load_dword v24, v[24:25], off offset:20
	s_waitcnt vmcnt(0)
	v_pk_mul_f32 v[18:19], v[18:19], v[24:25] op_sel_hi:[1,0]
	v_pk_mul_f32 v[16:17], v[16:17], v[24:25] op_sel_hi:[1,0]
; #define LAS __attribute__((address_space(3)))
; __device__ __forceinline__ bf16_t f2bf(float f) { unsigned u = __float_as_uint(f); u += 0x7FFFu + ((u >> 16) & 1u); return (bf16_t)(u >> 16); }
; __device__ __forceinline__ void conv_tile(LAS unsigned char* lds, const float* __restrict__ src, int Nsrc, bf16_t* __restrict__ dst, int K, int type, const float* __restrict__ ksc, int kt, int nt) {
;     ...
;     for (int i = 0; i < 8; ++i) { const int k = kt * 64 + kr + 8 * i; v[i] = (f32x4){0.f, 0.f, 0.f, 0.f};
;         if (sc >= 0) { v[i] = *(const f32x4*)(src + (size_t)k * Nsrc + sc); if (ksc) v[i] *= ksc[k]; } }
; #pragma unroll
;     for (int i = 0; i < 8; ++i) {
; #pragma unroll
;         for (int j = 0; j < 4; ++j) tile[(n4 + j) * 72 + kr + 8 * i] = f2bf(v[i][j]); }
;     __syncthreads();
; #pragma unroll
;     for (int e = 0; e < 4; ++e) { const int id = tid + e * NTHR, n2 = id >> 3, kc = id & 7;
;         const u32x4 w = *(const LAS u32x4*)(tile + n2 * 72 + kc * 8);
;         *(u32x4*)(dst + (size_t)(nt * 256 + n2) * K + kt * 64 + kc * 8) = w; }
;     __syncthreads();
.LBB0_949:
	s_or_b64 exec, exec, s[70:71]
	v_mov_b32_e32 v24, 0
	v_mov_b32_e32 v28, 0
	v_mov_b32_e32 v29, 0
	v_mov_b32_e32 v30, 0
	v_mov_b32_e32 v31, 0
	s_and_saveexec_b64 s[70:71], s[0:1]
	s_cbranch_execz .LBB0_952
	v_add_u32_e32 v25, 6, v32
	v_mad_i64_i32 v[26:27], s[78:79], s38, v25, 0
	v_lshl_add_u64 v[26:27], v[26:27], 2, v[34:35]
	global_load_dwordx4 v[28:31], v[26:27], off
	s_and_b64 vcc, exec, s[40:41]
	s_cbranch_vccnz .LBB0_952
	v_ashrrev_i32_e32 v33, 31, v32
	v_lshl_add_u64 v[26:27], v[32:33], 2, s[64:65]
	global_load_dword v26, v[26:27], off offset:24
	s_waitcnt vmcnt(0)
	v_pk_mul_f32 v[30:31], v[30:31], v[26:27] op_sel_hi:[1,0]
	v_pk_mul_f32 v[28:29], v[28:29], v[26:27] op_sel_hi:[1,0]
.LBB0_952:
	s_or_b64 exec, exec, s[70:71]
	v_mov_b32_e32 v25, 0
	v_mov_b32_e32 v26, 0
	v_mov_b32_e32 v27, 0
	s_and_saveexec_b64 s[70:71], s[0:1]
	s_cbranch_execz .LBB0_955
	v_add_u32_e32 v24, 7, v32
	v_mad_i64_i32 v[24:25], s[0:1], s38, v24, 0
	v_lshl_add_u64 v[24:25], v[24:25], 2, v[34:35]
	global_load_dwordx4 v[24:27], v[24:25], off
	s_and_b64 vcc, exec, s[40:41]
	s_cbranch_vccnz .LBB0_955
	v_ashrrev_i32_e32 v33, 31, v32
	v_lshl_add_u64 v[32:33], v[32:33], 2, s[64:65]
	global_load_dword v32, v[32:33], off offset:28
	s_waitcnt vmcnt(0)
	v_pk_mul_f32 v[26:27], v[26:27], v[32:33] op_sel_hi:[1,0]
	v_pk_mul_f32 v[24:25], v[24:25], v[32:33] op_sel_hi:[1,0]
.LBB0_955:
	s_or_b64 exec, exec, s[70:71]
	s_waitcnt vmcnt(0)
	v_lshlrev_b32_e32 v32, 4, v38
	v_mul_u32_u24_e32 v33, 0x90, v37
	v_add3_u32 v32, 0, v32, v33
	v_cvt_pk_bf16_f32 v40, v4, v0
	v_cvt_pk_bf16_f32 v41, v12, v8
	v_cvt_pk_bf16_f32 v42, v20, v16
	v_cvt_pk_bf16_f32 v43, v28, v24
	ds_write_b128 v32, v[40:43]
	v_cvt_pk_bf16_f32 v44, v5, v1
	v_cvt_pk_bf16_f32 v45, v13, v9
	v_cvt_pk_bf16_f32 v46, v21, v17
	v_cvt_pk_bf16_f32 v47, v29, v25
	ds_write_b128 v32, v[44:47] offset:144
	v_cvt_pk_bf16_f32 v48, v6, v2
	v_cvt_pk_bf16_f32 v49, v14, v10
	v_cvt_pk_bf16_f32 v50, v22, v18
	v_cvt_pk_bf16_f32 v51, v30, v26
	ds_write_b128 v32, v[48:51] offset:288
	v_cvt_pk_bf16_f32 v52, v7, v3
	v_cvt_pk_bf16_f32 v53, v15, v11
	v_cvt_pk_bf16_f32 v54, v23, v19
	v_cvt_pk_bf16_f32 v55, v31, v27
	ds_write_b128 v32, v[52:55] offset:432
	s_ashr_i32 s69, s68, 31
	v_lshlrev_b32_e32 v0, 4, v36
	s_lshl_b64 s[0:1], s[68:69], 1
	v_and_b32_e32 v208, 0x70, v0
	s_add_u32 s0, s26, s0
	v_add_u32_e32 v8, 0, v208
	s_addc_u32 s1, s27, s1
	v_ashrrev_i32_e32 v4, 3, v36
	v_lshl_add_u64 v[10:11], s[0:1], 0, v[208:209]
	v_mad_u64_u32 v[0:1], s[0:1], v4, s87, v[8:9]
	v_add_u32_e32 v4, s74, v4
	v_ashrrev_i32_e32 v7, 31, v4
	v_mad_u64_u32 v[4:5], s[0:1], v4, s31, 0
	v_mov_b32_e32 v6, v5
	s_waitcnt lgkmcnt(0)
	s_barrier
	ds_read_b128 v[0:3], v0
	v_mad_u64_u32 v[6:7], s[0:1], v7, s31, v[6:7]
	v_mov_b32_e32 v5, v6
	v_lshl_add_u64 v[12:13], v[4:5], 1, v[10:11]
	v_add_u32_e32 v4, 0x200, v36
	v_ashrrev_i32_e32 v9, 3, v4
	v_mad_u64_u32 v[4:5], s[0:1], v9, s87, v[8:9]
	ds_read_b128 v[4:7], v4
	s_waitcnt lgkmcnt(1)
	global_store_dwordx4 v[12:13], v[0:3], off
	s_nop 1
	v_add_u32_e32 v0, s74, v9
	v_ashrrev_i32_e32 v3, 31, v0
	v_mad_u64_u32 v[0:1], s[0:1], v0, s31, 0
	v_mov_b32_e32 v2, v1
	v_mad_u64_u32 v[2:3], s[0:1], v3, s31, v[2:3]
	v_mov_b32_e32 v1, v2
	v_lshl_add_u64 v[0:1], v[0:1], 1, v[10:11]
	s_waitcnt lgkmcnt(0)
	global_store_dwordx4 v[0:1], v[4:7], off
	v_add_u32_e32 v0, 0x400, v36
	s_nop 0
	v_ashrrev_i32_e32 v4, 3, v0
	v_mad_u64_u32 v[0:1], s[0:1], v4, s87, v[8:9]
	v_add_u32_e32 v4, s74, v4
	v_ashrrev_i32_e32 v7, 31, v4
	v_mad_u64_u32 v[4:5], s[0:1], v4, s31, 0
	v_mov_b32_e32 v6, v5
	ds_read_b128 v[0:3], v0
	v_mad_u64_u32 v[6:7], s[0:1], v7, s31, v[6:7]
	v_mov_b32_e32 v5, v6
	v_lshl_add_u64 v[12:13], v[4:5], 1, v[10:11]
	v_add_u32_e32 v4, 0x600, v36
	v_ashrrev_i32_e32 v9, 3, v4
	v_mad_u64_u32 v[4:5], s[0:1], v9, s87, v[8:9]
	ds_read_b128 v[4:7], v4
	s_waitcnt lgkmcnt(1)
	global_store_dwordx4 v[12:13], v[0:3], off
	s_nop 1
	v_add_u32_e32 v0, s74, v9
	v_ashrrev_i32_e32 v3, 31, v0
	v_mad_u64_u32 v[0:1], s[0:1], v0, s31, 0
	v_mov_b32_e32 v2, v1
	v_mad_u64_u32 v[2:3], s[0:1], v3, s31, v[2:3]
	v_mov_b32_e32 v1, v2
	v_lshl_add_u64 v[0:1], v[0:1], 1, v[10:11]
	s_mov_b64 s[0:1], 0
	s_waitcnt lgkmcnt(0)
	global_store_dwordx4 v[0:1], v[4:7], off
	s_barrier

; #define LAS __attribute__((address_space(3)))
; __device__ __forceinline__ void conv_tile(LAS unsigned char* lds, const float* __restrict__ src, int Nsrc, bf16_t* __restrict__ dst, int K, int type, const float* __restrict__ ksc, int kt, int nt) {
;     LAS bf16_t* tile = (LAS bf16_t*)lds;
;     int tid = threadIdx.x; asm volatile("" : "+v"(tid));
;     const int n4 = (tid & 63) * 4, kr = tid >> 6;
;     const int sc = wsrc_col(type, nt * 256 + n4);
;     f32x4 v[8];
; #pragma unroll
;     for (int i = 0; i < 8; ++i) { const int k = kt * 64 + kr + 8 * i; v[i] = (f32x4){0.f, 0.f, 0.f, 0.f};
;         if (sc >= 0) { v[i] = *(const f32x4*)(src + (size_t)k * Nsrc + sc); if (ksc) v[i] *= ksc[k]; } }
.LBB0_1039:
	s_mul_i32 s41, s41, s40
	s_sub_i32 s28, s3, s41
	s_lshl_b32 s28, s28, 6
	s_cmp_lg_u64 s[36:37], 0
	v_lshl_add_u64 v[34:35], v[208:209], 2, s[38:39]
	s_cselect_b64 s[38:39], -1, 0
	v_ashrrev_i32_e32 v38, 6, v36
	v_cndmask_b32_e64 v1, 0, 1, s[38:39]
	v_cmp_lt_i32_e64 s[0:1], -1, v208
	v_lshl_add_u32 v32, v38, 3, s28
	v_mov_b32_e32 v0, 0
	v_cmp_ne_u32_e64 s[40:41], 1, v1
	v_mov_b32_e32 v4, 0
	v_mov_b32_e32 v5, 0
	v_mov_b32_e32 v6, 0
	v_mov_b32_e32 v7, 0
	s_and_saveexec_b64 s[38:39], s[0:1]
	s_cbranch_execz .LBB0_1042
	v_mad_i64_i32 v[2:3], s[48:49], s44, v32, 0
	v_lshl_add_u64 v[2:3], v[2:3], 2, v[34:35]
	global_load_dwordx4 v[4:7], v[2:3], off
	s_and_b64 vcc, exec, s[40:41]
	s_cbranch_vccnz .LBB0_1042
	v_ashrrev_i32_e32 v33, 31, v32
	v_lshl_add_u64 v[2:3], v[32:33], 2, s[36:37]
	global_load_dword v2, v[2:3], off
	s_waitcnt vmcnt(0)
	v_pk_mul_f32 v[6:7], v[6:7], v[2:3] op_sel_hi:[1,0]
	v_pk_mul_f32 v[4:5], v[4:5], v[2:3] op_sel_hi:[1,0]
.LBB0_1042:
	s_or_b64 exec, exec, s[38:39]
	v_mov_b32_e32 v1, 0
	v_mov_b32_e32 v2, 0
	v_mov_b32_e32 v3, 0
	s_and_saveexec_b64 s[38:39], s[0:1]
	s_cbranch_execz .LBB0_1045
	v_add_u32_e32 v0, 1, v32
	v_mad_i64_i32 v[0:1], s[48:49], s44, v0, 0
	v_lshl_add_u64 v[0:1], v[0:1], 2, v[34:35]
	global_load_dwordx4 v[0:3], v[0:1], off
	s_and_b64 vcc, exec, s[40:41]
	s_cbranch_vccnz .LBB0_1045
	v_ashrrev_i32_e32 v33, 31, v32
	v_lshl_add_u64 v[8:9], v[32:33], 2, s[36:37]
	global_load_dword v8, v[8:9], off offset:4
	s_waitcnt vmcnt(0)
	v_pk_mul_f32 v[2:3], v[2:3], v[8:9] op_sel_hi:[1,0]
	v_pk_mul_f32 v[0:1], v[0:1], v[8:9] op_sel_hi:[1,0]
.LBB0_1045:
	s_or_b64 exec, exec, s[38:39]
	v_mov_b32_e32 v8, 0
	v_mov_b32_e32 v12, 0
	v_mov_b32_e32 v13, 0
	v_mov_b32_e32 v14, 0
	v_mov_b32_e32 v15, 0
	s_and_saveexec_b64 s[38:39], s[0:1]
	s_cbranch_execz .LBB0_1048
	v_add_u32_e32 v9, 2, v32
	v_mad_i64_i32 v[10:11], s[48:49], s44, v9, 0
	v_lshl_add_u64 v[10:11], v[10:11], 2, v[34:35]
	global_load_dwordx4 v[12:15], v[10:11], off
	s_and_b64 vcc, exec, s[40:41]
	s_cbranch_vccnz .LBB0_1048
	v_ashrrev_i32_e32 v33, 31, v32
	v_lshl_add_u64 v[10:11], v[32:33], 2, s[36:37]
	global_load_dword v10, v[10:11], off offset:8
	s_waitcnt vmcnt(0)
	v_pk_mul_f32 v[14:15], v[14:15], v[10:11] op_sel_hi:[1,0]
	v_pk_mul_f32 v[12:13], v[12:13], v[10:11] op_sel_hi:[1,0]
.LBB0_1048:
	s_or_b64 exec, exec, s[38:39]
	v_mov_b32_e32 v9, 0
	v_mov_b32_e32 v10, 0
	v_mov_b32_e32 v11, 0
	s_and_saveexec_b64 s[38:39], s[0:1]
	s_cbranch_execz .LBB0_1051
	v_add_u32_e32 v8, 3, v32
	v_mad_i64_i32 v[8:9], s[48:49], s44, v8, 0
	v_lshl_add_u64 v[8:9], v[8:9], 2, v[34:35]
	global_load_dwordx4 v[8:11], v[8:9], off
	s_and_b64 vcc, exec, s[40:41]
	s_cbranch_vccnz .LBB0_1051
	v_ashrrev_i32_e32 v33, 31, v32
	v_lshl_add_u64 v[16:17], v[32:33], 2, s[36:37]
	global_load_dword v16, v[16:17], off offset:12
	s_waitcnt vmcnt(0)
	v_pk_mul_f32 v[10:11], v[10:11], v[16:17] op_sel_hi:[1,0]
	v_pk_mul_f32 v[8:9], v[8:9], v[16:17] op_sel_hi:[1,0]
.LBB0_1051:
	s_or_b64 exec, exec, s[38:39]
	v_mov_b32_e32 v16, 0
	v_mov_b32_e32 v20, 0
	v_mov_b32_e32 v21, 0
	v_mov_b32_e32 v22, 0
	v_mov_b32_e32 v23, 0
	s_and_saveexec_b64 s[38:39], s[0:1]
	s_cbranch_execz .LBB0_1054
	v_add_u32_e32 v17, 4, v32
	v_mad_i64_i32 v[18:19], s[48:49], s44, v17, 0
	v_lshl_add_u64 v[18:19], v[18:19], 2, v[34:35]
	global_load_dwordx4 v[20:23], v[18:19], off
	s_and_b64 vcc, exec, s[40:41]
	s_cbranch_vccnz .LBB0_1054
	v_ashrrev_i32_e32 v33, 31, v32
	v_lshl_add_u64 v[18:19], v[32:33], 2, s[36:37]
	global_load_dword v18, v[18:19], off offset:16
	s_waitcnt vmcnt(0)
	v_pk_mul_f32 v[22:23], v[22:23], v[18:19] op_sel_hi:[1,0]
	v_pk_mul_f32 v[20:21], v[20:21], v[18:19] op_sel_hi:[1,0]
.LBB0_1054:
	s_or_b64 exec, exec, s[38:39]
	v_mov_b32_e32 v17, 0
	v_mov_b32_e32 v18, 0
	v_mov_b32_e32 v19, 0
	s_and_saveexec_b64 s[38:39], s[0:1]
	s_cbranch_execz .LBB0_1057
	v_add_u32_e32 v16, 5, v32
	v_mad_i64_i32 v[16:17], s[48:49], s44, v16, 0
	v_lshl_add_u64 v[16:17], v[16:17], 2, v[34:35]
	global_load_dwordx4 v[16:19], v[16:17], off
	s_and_b64 vcc, exec, s[40:41]
	s_cbranch_vccnz .LBB0_1057
	v_ashrrev_i32_e32 v33, 31, v32
	v_lshl_add_u64 v[24:25], v[32:33], 2, s[36:37]
	global_load_dword v24, v[24:25], off offset:20
	s_waitcnt vmcnt(0)
	v_pk_mul_f32 v[18:19], v[18:19], v[24:25] op_sel_hi:[1,0]
	v_pk_mul_f32 v[16:17], v[16:17], v[24:25] op_sel_hi:[1,0]
; #define LAS __attribute__((address_space(3)))
; __device__ __forceinline__ bf16_t f2bf(float f) { unsigned u = __float_as_uint(f); u += 0x7FFFu + ((u >> 16) & 1u); return (bf16_t)(u >> 16); }
; __device__ __forceinline__ void conv_tile(LAS unsigned char* lds, const float* __restrict__ src, int Nsrc, bf16_t* __restrict__ dst, int K, int type, const float* __restrict__ ksc, int kt, int nt) {
;     ...
;     for (int i = 0; i < 8; ++i) { const int k = kt * 64 + kr + 8 * i; v[i] = (f32x4){0.f, 0.f, 0.f, 0.f};
;         if (sc >= 0) { v[i] = *(const f32x4*)(src + (size_t)k * Nsrc + sc); if (ksc) v[i] *= ksc[k]; } }
; #pragma unroll
;     for (int i = 0; i < 8; ++i) {
; #pragma unroll
;         for (int j = 0; j < 4; ++j) tile[(n4 + j) * 72 + kr + 8 * i] = f2bf(v[i][j]); }
;     __syncthreads();
; #pragma unroll
;     for (int e = 0; e < 4; ++e) { const int id = tid + e * NTHR, n2 = id >> 3, kc = id & 7;
;         const u32x4 w = *(const LAS u32x4*)(tile + n2 * 72 + kc * 8);
;         *(u32x4*)(dst + (size_t)(nt * 256 + n2) * K + kt * 64 + kc * 8) = w; }
;     __syncthreads();
.LBB0_1057:
	s_or_b64 exec, exec, s[38:39]
	v_mov_b32_e32 v24, 0
	v_mov_b32_e32 v28, 0
	v_mov_b32_e32 v29, 0
	v_mov_b32_e32 v30, 0
	v_mov_b32_e32 v31, 0
	s_and_saveexec_b64 s[38:39], s[0:1]
	s_cbranch_execz .LBB0_1060
	v_add_u32_e32 v25, 6, v32
	v_mad_i64_i32 v[26:27], s[48:49], s44, v25, 0
	v_lshl_add_u64 v[26:27], v[26:27], 2, v[34:35]
	global_load_dwordx4 v[28:31], v[26:27], off
	s_and_b64 vcc, exec, s[40:41]
	s_cbranch_vccnz .LBB0_1060
	v_ashrrev_i32_e32 v33, 31, v32
	v_lshl_add_u64 v[26:27], v[32:33], 2, s[36:37]
	global_load_dword v26, v[26:27], off offset:24
	s_waitcnt vmcnt(0)
	v_pk_mul_f32 v[30:31], v[30:31], v[26:27] op_sel_hi:[1,0]
	v_pk_mul_f32 v[28:29], v[28:29], v[26:27] op_sel_hi:[1,0]
.LBB0_1060:
	s_or_b64 exec, exec, s[38:39]
	v_mov_b32_e32 v25, 0
	v_mov_b32_e32 v26, 0
	v_mov_b32_e32 v27, 0
	s_and_saveexec_b64 s[38:39], s[0:1]
	s_cbranch_execz .LBB0_1063
	v_add_u32_e32 v24, 7, v32
	v_mad_i64_i32 v[24:25], s[0:1], s44, v24, 0
	v_lshl_add_u64 v[24:25], v[24:25], 2, v[34:35]
	global_load_dwordx4 v[24:27], v[24:25], off
	s_and_b64 vcc, exec, s[40:41]
	s_cbranch_vccnz .LBB0_1063
	v_ashrrev_i32_e32 v33, 31, v32
	v_lshl_add_u64 v[32:33], v[32:33], 2, s[36:37]
	global_load_dword v32, v[32:33], off offset:28
	s_waitcnt vmcnt(0)
	v_pk_mul_f32 v[26:27], v[26:27], v[32:33] op_sel_hi:[1,0]
	v_pk_mul_f32 v[24:25], v[24:25], v[32:33] op_sel_hi:[1,0]
.LBB0_1063:
	s_or_b64 exec, exec, s[38:39]
	s_waitcnt vmcnt(0)
	v_lshlrev_b32_e32 v32, 4, v38
	v_mul_u32_u24_e32 v33, 0x90, v37
	v_add3_u32 v32, 0, v32, v33
	v_cvt_pk_bf16_f32 v40, v4, v0
	v_cvt_pk_bf16_f32 v41, v12, v8
	v_cvt_pk_bf16_f32 v42, v20, v16
	v_cvt_pk_bf16_f32 v43, v28, v24
	ds_write_b128 v32, v[40:43]
	v_cvt_pk_bf16_f32 v44, v5, v1
	v_cvt_pk_bf16_f32 v45, v13, v9
	v_cvt_pk_bf16_f32 v46, v21, v17
	v_cvt_pk_bf16_f32 v47, v29, v25
	ds_write_b128 v32, v[44:47] offset:144
	v_cvt_pk_bf16_f32 v48, v6, v2
	v_cvt_pk_bf16_f32 v49, v14, v10
	v_cvt_pk_bf16_f32 v50, v22, v18
	v_cvt_pk_bf16_f32 v51, v30, v26
	ds_write_b128 v32, v[48:51] offset:288
	v_cvt_pk_bf16_f32 v52, v7, v3
	v_cvt_pk_bf16_f32 v53, v15, v11
	v_cvt_pk_bf16_f32 v54, v23, v19
	v_cvt_pk_bf16_f32 v55, v31, v27
	ds_write_b128 v32, v[52:55] offset:432
	s_ashr_i32 s29, s28, 31
	v_lshlrev_b32_e32 v0, 4, v36
	s_lshl_b64 s[0:1], s[28:29], 1
	v_and_b32_e32 v208, 0x70, v0
	s_add_u32 s0, s26, s0
	v_add_u32_e32 v8, 0, v208
	s_addc_u32 s1, s27, s1
	v_ashrrev_i32_e32 v4, 3, v36
	v_lshl_add_u64 v[10:11], s[0:1], 0, v[208:209]
	v_mad_u64_u32 v[0:1], s[0:1], v4, s87, v[8:9]
	v_add_u32_e32 v4, s46, v4
	v_ashrrev_i32_e32 v7, 31, v4
	v_mad_u64_u32 v[4:5], s[0:1], v4, s31, 0
	v_mov_b32_e32 v6, v5
	s_waitcnt lgkmcnt(0)
	s_barrier
	ds_read_b128 v[0:3], v0
	v_mad_u64_u32 v[6:7], s[0:1], v7, s31, v[6:7]
	v_mov_b32_e32 v5, v6
	v_lshl_add_u64 v[12:13], v[4:5], 1, v[10:11]
	v_add_u32_e32 v4, 0x200, v36
	v_ashrrev_i32_e32 v9, 3, v4
	v_mad_u64_u32 v[4:5], s[0:1], v9, s87, v[8:9]
	ds_read_b128 v[4:7], v4
	s_waitcnt lgkmcnt(1)
	global_store_dwordx4 v[12:13], v[0:3], off
	s_nop 1
	v_add_u32_e32 v0, s46, v9
	v_ashrrev_i32_e32 v3, 31, v0
	v_mad_u64_u32 v[0:1], s[0:1], v0, s31, 0
	v_mov_b32_e32 v2, v1
	v_mad_u64_u32 v[2:3], s[0:1], v3, s31, v[2:3]
	v_mov_b32_e32 v1, v2
	v_lshl_add_u64 v[0:1], v[0:1], 1, v[10:11]
	s_waitcnt lgkmcnt(0)
	global_store_dwordx4 v[0:1], v[4:7], off
	v_add_u32_e32 v0, 0x400, v36
	s_nop 0
	v_ashrrev_i32_e32 v4, 3, v0
	v_mad_u64_u32 v[0:1], s[0:1], v4, s87, v[8:9]
	v_add_u32_e32 v4, s46, v4
	v_ashrrev_i32_e32 v7, 31, v4
	v_mad_u64_u32 v[4:5], s[0:1], v4, s31, 0
	v_mov_b32_e32 v6, v5
	ds_read_b128 v[0:3], v0
	v_mad_u64_u32 v[6:7], s[0:1], v7, s31, v[6:7]
	v_mov_b32_e32 v5, v6
	v_lshl_add_u64 v[12:13], v[4:5], 1, v[10:11]
	v_add_u32_e32 v4, 0x600, v36
	v_ashrrev_i32_e32 v9, 3, v4
	v_mad_u64_u32 v[4:5], s[0:1], v9, s87, v[8:9]
	ds_read_b128 v[4:7], v4
	s_waitcnt lgkmcnt(1)
	global_store_dwordx4 v[12:13], v[0:3], off
	s_nop 1
	v_add_u32_e32 v0, s46, v9
	v_ashrrev_i32_e32 v3, 31, v0
	v_mad_u64_u32 v[0:1], s[0:1], v0, s31, 0
	v_mov_b32_e32 v2, v1
	v_mad_u64_u32 v[2:3], s[0:1], v3, s31, v[2:3]
	v_mov_b32_e32 v1, v2
	v_lshl_add_u64 v[0:1], v[0:1], 1, v[10:11]
	s_mov_b64 s[0:1], 0
	s_waitcnt lgkmcnt(0)
	global_store_dwordx4 v[0:1], v[4:7], off
	s_barrier
